# attention work queue: next unit index reserved one unit ahead (atomic latency hidden), LDS broadcast of the index with ds ops instead of flat ops
# baseline (speedup 1.0000x reference)
;     unsigned* counter = (unsigned*)(p.ws + OFF_CTL) + 2 * rep;
;     volatile int* su = (volatile int*)(lds + LDS_UNIT);
;     if (which & 1) for (;;) {
.Lp3s_nosig:
.LBB0_456:
	s_cmp_gt_i32 s90, 4
	s_cselect_b64 s[0:1], -1, 0
	s_cmp_lt_i32 s91, 5
	s_cselect_b64 s[2:3], -1, 0
	s_or_b64 s[0:1], s[0:1], s[2:3]
	s_and_b64 vcc, exec, s[0:1]
	s_cbranch_vccnz .LBB0_627
	v_and_b32_e32 v1, 0x3ff, v0
	v_readfirstlane_b32 s54, v0
	s_bfe_u32 s54, s54, 0x10008

;     int tid_ = threadIdx.x; asm volatile("" : "+v"(tid_));
;     const int lane = tid_ & 63, w = tid_ >> 6, r = lane & 31, h = lane >> 5;
;     const int qt = 15 - (u >> 5), bh = u & 31, b = bh >> 2, hh = bh & 3;
;     const int q0 = qt * 256, wq0 = q0 + 32 * w, qpos = wq0 + r;
;     const int ntl = 4 * qt + 4;
;     const float lam = ((const float*)(p.ws + OFF_CTL))[16];
;     const bf16_t* VTb = (const bf16_t*)(p.ws + OFF_VDT) + (size_t)(b * 4 + hh) * 128 * 4096;
; #pragma unroll 1
;     for (int mp = 0; mp < 2; ++mp) {
;         const size_t hoff = ((size_t)(b * 8 + hh * 2 + mp) * 4096) * 64;
;         const bf16_t* Qb = (const bf16_t*)(p.ws + OFF_QD) + hoff;
;         const bf16_t* Kb = (const bf16_t*)(p.ws + OFF_KD) + hoff;
;     ...
;     if (which & 1) for (;;) {
;         if (threadIdx.x == 0) *su = (int)atomicAdd(counter, 1u);
	s_add_u32 s8, s88, 0xdba5800
	v_lshlrev_b32_e32 v158, 3, v1
	v_lshlrev_b32_e32 v2, 4, v1
	v_or_b32_e32 v6, 0x200, v1
	s_addc_u32 s9, s89, 0
	v_bfe_u32 v187, v0, 3, 7
	v_and_b32_e32 v196, 0x60, v2
	v_and_b32_e32 v197, 8, v158
	v_lshrrev_b32_e32 v6, 3, v6
	s_add_u32 s10, s88, 0xfba5800
	v_mov_b32_e32 v3, 0
	s_movk_i32 s2, 0x90
	v_mul_u32_u24_e32 v159, 0x90, v187
	v_add3_u32 v5, 0, v196, v197
	v_mul_u32_u24_e32 v180, 0x90, v6
	s_addc_u32 s11, s89, 0
	s_mov_b64 s[6:7], src_shared_base
	v_and_b32_e32 v4, 56, v158
	v_mad_u32_u24 v194, v187, s2, 0
	v_and_b32_e32 v195, 0x70, v2
	v_lshl_add_u64 v[6:7], s[88:89], 0, v[2:3]
	s_mov_b64 s[2:3], 0x11ba5800
	s_add_u32 s12, s88, 0x5ba5800
	v_add_u32_e32 v2, v5, v159
	v_add_u32_e32 v5, v5, v180
	v_cmp_eq_u32_e64 s[0:1], 0, v1
	v_lshlrev_b32_e32 v170, 7, v187
	v_mov_b32_e32 v171, v3
	s_movk_i32 s26, 0x200
	v_lshl_add_u64 v[160:161], v[6:7], 0, s[2:3]
	s_addc_u32 s13, s89, 0
	s_mov_b64 s[14:15], 0
	s_add_i32 s33, 0, 0x24010
	s_mov_b64 s[16:17], 0x2000
	v_add_u32_e32 v198, v194, v195
	s_mov_b32 s6, 0x3e38aa3b
	s_mov_b32 s27, 0x40e66666
	v_mov_b32_e32 v181, 0x358637bd
	s_mov_b32 s28, 0x800000
	v_lshlrev_b32_e32 v172, 1, v4
	v_add_u32_e32 v182, 0x2000, v2
	v_add_u32_e32 v183, 0x2000, v5
	v_mov_b32_e32 v184, 0xff800000
	s_and_saveexec_b64 s[2:3], s[0:1]
	v_mov_b32_e32 v239, 1
	global_atomic_add v239, v3, v239, s[88:89] sc0
	s_or_b64 exec, exec, s[2:3]
	s_branch .LBB0_460

;     int tid_ = threadIdx.x; asm volatile("" : "+v"(tid_));
;     const int lane = tid_ & 63, w = tid_ >> 6, r = lane & 31, h = lane >> 5;
;     const int qt = 15 - (u >> 5), bh = u & 31, b = bh >> 2, hh = bh & 3;
;     const int q0 = qt * 256, wq0 = q0 + 32 * w, qpos = wq0 + r;
;     const int ntl = 4 * qt + 4;
;     const float lam = ((const float*)(p.ws + OFF_CTL))[16];
;     const bf16_t* VTb = (const bf16_t*)(p.ws + OFF_VDT) + (size_t)(b * 4 + hh) * 128 * 4096;
; #pragma unroll 1
;     for (int mp = 0; mp < 2; ++mp) {
;         const size_t hoff = ((size_t)(b * 8 + hh * 2 + mp) * 4096) * 64;
;         const bf16_t* Qb = (const bf16_t*)(p.ws + OFF_QD) + hoff;
;         const bf16_t* Kb = (const bf16_t*)(p.ws + OFF_KD) + hoff;
;         bf16x8 qf[4];
; #pragma unroll
;         for (int s = 0; s < 4; ++s) qf[s] = *(const bf16x8*)(Qb + (size_t)qpos * 64 + s * 16 + h * 8);
;     ...
;     if (which & 1) for (;;) {
;         if (threadIdx.x == 0) *su = (int)atomicAdd(counter, 1u);
;         __syncthreads();
;         const int u = *su;
;         __syncthreads();
;         if (u >= 512) break;
;         diff_unit(p, u, lds, probe);
.LBB0_460:
	s_and_saveexec_b64 s[2:3], s[0:1]
	s_cbranch_execz .LBB0_464
	s_waitcnt vmcnt(0)
	v_mov_b32_e32 v2, v239
	v_mov_b32_e32 v239, 1
	global_atomic_add v239, v3, v239, s[88:89] sc0
	v_mov_b32_e32 v4, s33
	ds_write_b32 v4, v2
.LBB0_464:
	s_or_b64 exec, exec, s[2:3]
	s_cmp_lg_u32 s33, -1
	s_cselect_b32 s2, s33, 0
	s_cselect_b32 s3, s7, 0
	v_mov_b32_e32 v4, s2
	v_mov_b32_e32 v5, s3
	s_waitcnt lgkmcnt(0)
	s_barrier
	ds_read_b32 v4, v4
	s_mov_b64 s[2:3], -1
	s_waitcnt lgkmcnt(0)
	s_barrier
	v_cmp_gt_i32_e32 vcc, s26, v4
	s_and_saveexec_b64 s[18:19], vcc
	s_cbranch_execz .LBB0_459
	v_mov_b32_e32 v2, v1
	global_load_dword v185, v3, s[88:89] offset:64
	v_and_b32_e32 v8, 31, v2
	v_bfe_u32 v9, v2, 5, 1
	v_ashrrev_i32_e32 v5, 5, v4
	v_ashrrev_i32_e32 v2, 1, v2
	v_sub_u32_e32 v5, 15, v5
	v_and_b32_e32 v2, 0xffffffe0, v2
	v_bfe_u32 v10, v4, 2, 3
	v_and_b32_e32 v11, 3, v4
	v_lshl_add_u32 v186, v5, 8, v2
	v_lshlrev_b32_e32 v4, 20, v4
	v_or_b32_e32 v162, v186, v8
	v_lshl_add_u32 v188, v5, 2, 4
	v_and_b32_e32 v4, 0x1f00000, v4
	v_mov_b32_e32 v5, v3
	v_ashrrev_i32_e32 v163, 31, v162
	v_lshl_add_u64 v[164:165], v[160:161], 0, v[4:5]
	v_lshlrev_b32_e32 v4, 12, v10
	v_lshlrev_b64 v[6:7], 7, v[162:163]
	v_lshl_add_u64 v[4:5], v[162:163], 0, v[4:5]
	v_lshlrev_b32_e32 v168, 4, v9
	v_lshlrev_b64 v[4:5], 11, v[4:5]
	v_lshl_add_u64 v[6:7], s[8:9], 0, v[6:7]
	v_mov_b32_e32 v169, v3
	v_lshlrev_b32_e32 v2, 19, v11
	v_lshl_add_u64 v[174:175], v[6:7], 0, v[168:169]
	v_lshl_add_u64 v[4:5], s[12:13], 0, v[4:5]
	v_lshlrev_b32_e32 v6, 8, v11
	v_mov_b32_e32 v7, v3
	v_readlane_b32 s36, v238, 15
	v_lshl_or_b32 v189, v10, 21, v2
	v_lshlrev_b32_e32 v2, 3, v9
	v_lshl_add_u64 v[4:5], v[4:5], 0, v[6:7]
	v_readlane_b32 s50, v238, 29
	v_readlane_b32 s51, v238, 30
	v_lshl_add_u64 v[166:167], v[164:165], 0, s[16:17]
	v_or_b32_e32 v190, 31, v186
	v_mul_u32_u24_e32 v191, 0x90, v8
	v_lshlrev_b32_e32 v192, 2, v9
	v_lshl_add_u64 v[176:177], v[4:5], 0, v[2:3]
	v_lshl_add_u64 v[178:179], s[50:51], 0, v[168:169]
	s_mov_b32 s4, 0
	v_readlane_b32 s37, v238, 16
	v_readlane_b32 s38, v238, 17
	v_readlane_b32 s39, v238, 18
	v_readlane_b32 s40, v238, 19
	v_readlane_b32 s41, v238, 20
	v_readlane_b32 s42, v238, 21
	v_readlane_b32 s43, v238, 22
	v_readlane_b32 s44, v238, 23
	v_readlane_b32 s45, v238, 24
	v_readlane_b32 s46, v238, 25
	v_readlane_b32 s47, v238, 26
	v_readlane_b32 s48, v238, 27
	v_readlane_b32 s49, v238, 28
	s_branch .LBB0_467

;     int tid_ = threadIdx.x; asm volatile("" : "+v"(tid_));
;     const int lane = tid_ & 63, w = tid_ >> 6, r = lane & 31, h = lane >> 5;
;     const int qt = 63 - (u >> 4), bg = u & 15, b = bg >> 1, g = bg & 1;
;     const int hq = w >> 2, q0 = qt * 64, qb = q0 + 32 * hq, qpos = qb + r, head = g * 4 + (w & 3);
;     float* IMPW = (float*)(lds + NSA_IMPW);
;     u64* SEL = (u64*)(lds + NSA_SEL);
;     u64* UN = (u64*)(lds + NSA_UN);
;     const bf16_t* Qb = (const bf16_t*)(p.ws + OFF_QN) + ((size_t)(b * 8 + head) * 4096) * 64;
;     bf16x8 qf[4];
; #pragma unroll
;     for (int s = 0; s < 4; ++s) qf[s] = *(const bf16x8*)(Qb + (size_t)qpos * 64 + s * 16 + h * 8);
; #pragma unroll
;     for (int s = 0; s < 4; ++s) asm volatile("" : "+v"(qf[s]));
;     const float* gp = (const float*)(p.ws + OFF_GATES) + ((size_t)b * 4096 + qpos) * 24 + head * 3;
;     auto inc = [](int j) { return j + 1; };
;     f32x16 oacc[2];
;     float* FT = (float*)(lds + NSA_FT);
;     {
;         const bf16_t* Kc = (const bf16_t*)(p.ws + OFF_KCMP) + (size_t)bg * 256 * 64;
;     ...
;     if (which & 2) for (;;) {
;         if (threadIdx.x == 0) *su = (int)atomicAdd(counter + 1, 1u);
.Lp4n_go:
	buffer_inv sc1
	s_add_u32 s2, s88, 0x13ba5800
	s_addc_u32 s3, s89, 0
	v_writelane_b32 v238, s2, 47
	v_mov_b32_e32 v173, 0
	v_lshlrev_b32_e32 v174, 1, v158
	v_writelane_b32 v238, s3, 48
	s_add_u32 s2, s88, 0x192a5800
	s_addc_u32 s3, s89, 0
	v_writelane_b32 v238, s2, 49
	v_mov_b32_e32 v175, v173
	s_add_u32 s76, s88, 0x18ba5800
	v_writelane_b32 v238, s3, 50
	v_lshl_add_u64 v[2:3], s[88:89], 0, v[174:175]
	s_mov_b64 s[2:3], 0x19325800
	s_addc_u32 s77, s89, 0
	v_lshl_add_u64 v[176:177], v[2:3], 0, s[2:3]
	s_add_u32 s2, s88, 0x173a5800
	s_addc_u32 s3, s89, 0
	v_writelane_b32 v238, s2, 51
	v_add_u32_e32 v4, v194, v196
	s_mov_b64 s[70:71], src_shared_base
	v_writelane_b32 v238, s3, 52
	s_add_u32 s2, s88, 0x16ba5800
	s_addc_u32 s3, s89, 0
	s_add_u32 s82, s88, 0x17ba5800
	s_addc_u32 s83, s89, 0
	v_writelane_b32 v238, s2, 53
	s_add_u32 s96, s88, 0x183a5800
	s_addc_u32 s97, s89, 0
	v_writelane_b32 v238, s3, 54
	s_add_i32 s2, 0, 0x19210
	v_add_u32_e32 v2, v4, v197
	v_writelane_b32 v238, s2, 55
	s_add_i32 s2, 0, 0x19220
	s_mov_b64 s[92:93], 0
	s_mov_b32 s69, 0
	s_add_i32 s74, 0, 0x19240
	s_mov_b32 s70, 0x3e38aa3b
	s_add_i32 s75, 0, 0x19000
	v_writelane_b32 v238, s2, 56
	s_add_i32 s2, 0, 0x19230
	s_mov_b32 s78, 0x40e66666
	v_add_u32_e32 v199, 0x2000, v2
	v_mov_b32_e32 v200, 0xff800000
	v_mov_b32_e32 v201, 0x7f800000
	v_writelane_b32 v238, s2, 57
	s_and_saveexec_b64 s[2:3], s[0:1]
	v_mov_b32_e32 v239, 1
	global_atomic_add v239, v173, v239, s[88:89] offset:4 sc0
	s_or_b64 exec, exec, s[2:3]
	s_branch .LBB0_486

;     int tid_ = threadIdx.x; asm volatile("" : "+v"(tid_));
;     const int lane = tid_ & 63, w = tid_ >> 6, r = lane & 31, h = lane >> 5;
;     const int qt = 63 - (u >> 4), bg = u & 15, b = bg >> 1, g = bg & 1;
;     const int hq = w >> 2, q0 = qt * 64, qb = q0 + 32 * hq, qpos = qb + r, head = g * 4 + (w & 3);
;     float* IMPW = (float*)(lds + NSA_IMPW);
;     u64* SEL = (u64*)(lds + NSA_SEL);
;     u64* UN = (u64*)(lds + NSA_UN);
;     const bf16_t* Qb = (const bf16_t*)(p.ws + OFF_QN) + ((size_t)(b * 8 + head) * 4096) * 64;
;     bf16x8 qf[4];
; #pragma unroll
;     for (int s = 0; s < 4; ++s) qf[s] = *(const bf16x8*)(Qb + (size_t)qpos * 64 + s * 16 + h * 8);
; #pragma unroll
;     for (int s = 0; s < 4; ++s) asm volatile("" : "+v"(qf[s]));
;     const float* gp = (const float*)(p.ws + OFF_GATES) + ((size_t)b * 4096 + qpos) * 24 + head * 3;
;     auto inc = [](int j) { return j + 1; };
;     f32x16 oacc[2];
;     float* FT = (float*)(lds + NSA_FT);
;     {
;         const bf16_t* Kc = (const bf16_t*)(p.ws + OFF_KCMP) + (size_t)bg * 256 * 64;
;         const bf16_t* VcT = (const bf16_t*)(p.ws + OFF_VCMPT) + (size_t)bg * 64 * 256;
;         const int nmax = ((q0 + 32) >> 4) + 1, ntc = (nmax + 63) >> 6;
;         const int nvalid = qpos >= 31 ? ((qpos - 31) >> 4) + 1 : 0;
;         float m = -1e30f, l = 0.f, carry = 0.f;
;         f32x16 oc[2];
; #pragma unroll
;         for (int dt = 0; dt < 2; ++dt)
; #pragma unroll
;             for (int i = 0; i < 16; ++i) oc[dt][i] = 0.f;
;         kv_loop<64, true>(lds, Kc, VcT, 256, ntc, 0, inc, [&](int j, const unsigned char* sb) {
;     ...
;     if (which & 2) for (;;) {
;         if (threadIdx.x == 0) *su = (int)atomicAdd(counter + 1, 1u);
;         __syncthreads();
;         const int u = *su;
;         __syncthreads();
;         if (u >= 1024) break;
;         nsa_unit(p, u, lds, probe);
.LBB0_486:
	s_and_saveexec_b64 s[4:5], s[0:1]
	s_cbranch_execz .LBB0_490
	s_waitcnt vmcnt(0)
	v_mov_b32_e32 v4, v239
	v_mov_b32_e32 v239, 1
	global_atomic_add v239, v173, v239, s[88:89] offset:4 sc0
	v_mov_b32_e32 v2, s33
	ds_write_b32 v2, v4
.LBB0_490:
	s_or_b64 exec, exec, s[4:5]
	s_cmp_lg_u32 s33, -1
	s_cselect_b32 s2, s33, 0
	s_cselect_b32 s3, s71, 0
	v_mov_b32_e32 v2, s2
	v_mov_b32_e32 v3, s3
	s_waitcnt lgkmcnt(0)
	s_barrier
	ds_read_b32 v2, v2
	s_movk_i32 s2, 0x400
	s_mov_b64 s[4:5], -1
	s_waitcnt lgkmcnt(0)
	s_barrier
	v_cmp_gt_i32_e32 vcc, s2, v2
	s_and_saveexec_b64 s[94:95], vcc
	s_cbranch_execz .LBB0_485
	v_mov_b32_e32 v17, v1
	v_lshlrev_b32_e32 v3, 2, v2
	v_ashrrev_i32_e32 v82, 6, v17
	v_and_b32_e32 v130, 0xffffffc0, v3
	v_lshlrev_b32_e32 v83, 3, v82
	v_sub_u32_e32 v123, 0xfc0, v130
	v_and_b32_e32 v81, 0xffffffe0, v83
	v_and_b32_e32 v80, 31, v17
	v_bfe_u32 v85, v2, 1, 3
	v_add_u32_e32 v203, v81, v123
	v_and_b32_e32 v3, 4, v3
	v_or_b32_e32 v178, v203, v80
	v_and_or_b32 v202, v82, 3, v3
	v_lshlrev_b32_e32 v3, 22, v85
	v_readlane_b32 s2, v238, 47
	v_lshl_or_b32 v4, v202, 19, v3
	v_mov_b32_e32 v5, v173
	v_readlane_b32 s3, v238, 48
	v_ashrrev_i32_e32 v179, 31, v178
	v_bfe_u32 v36, v17, 5, 1
	v_lshl_add_u64 v[4:5], s[2:3], 0, v[4:5]
	v_lshlrev_b64 v[6:7], 7, v[178:179]
	v_lshl_add_u64 v[4:5], v[4:5], 0, v[6:7]
	v_lshlrev_b32_e32 v180, 4, v36
	v_mov_b32_e32 v181, v173
	v_lshl_add_u64 v[4:5], v[4:5], 0, v[180:181]
	global_load_dwordx4 v[146:149], v[4:5], off
	global_load_dwordx4 v[150:153], v[4:5], off offset:32
	global_load_dwordx4 v[154:157], v[4:5], off offset:64
	global_load_dwordx4 v[158:161], v[4:5], off offset:96
	v_and_b32_e32 v122, 15, v2
	v_readlane_b32 s2, v238, 49
	v_mov_b32_e32 v3, v173
	v_lshlrev_b32_e32 v2, 15, v122
	v_readlane_b32 s3, v238, 50
	v_lshl_add_u64 v[74:75], v[176:177], 0, v[2:3]
	v_and_b32_e32 v84, 63, v17
	v_lshl_add_u64 v[34:35], s[2:3], 0, v[2:3]
	v_lshl_add_u64 v[2:3], v[34:35], 0, v[170:171]
	v_lshl_add_u64 v[2:3], v[2:3], 0, v[172:173]
	v_lshrrev_b32_e32 v17, 4, v123
	v_add_u32_e32 v17, 64, v17
	v_lshrrev_b32_e32 v90, 6, v17
	v_subrev_u32_e32 v17, 31, v178
	v_ashrrev_i32_e32 v17, 4, v17
	v_mov_b32_e32 v88, 0
	v_lshl_add_u64 v[76:77], v[34:35], 0, v[172:173]
	v_lshlrev_b32_e32 v181, 2, v36
	v_lshl_add_u32 v34, v82, 13, 0
	v_lshlrev_b32_e32 v35, 8, v80
	v_lshlrev_b32_e32 v36, 4, v80
	v_lshlrev_b32_e32 v37, 9, v82
	v_add_u32_e32 v17, 1, v17
	v_cmp_lt_i32_e32 vcc, 30, v178
	v_mov_b32_e32 v93, 0xf149f2ca
	s_mov_b64 s[72:73], 0
	s_mov_b32 s2, 0
	v_mov_b32_e32 v92, 0
	v_mov_b32_e32 v94, 0
	v_mov_b32_e32 v18, 0
	v_mov_b32_e32 v19, v88
	v_mov_b32_e32 v20, v88
	v_mov_b32_e32 v21, v88
	v_mov_b32_e32 v22, v88
	v_mov_b32_e32 v23, v88
	v_mov_b32_e32 v24, v88
	v_mov_b32_e32 v25, v88
	v_mov_b32_e32 v26, v88
	v_mov_b32_e32 v27, v88
	v_mov_b32_e32 v28, v88
	v_mov_b32_e32 v29, v88
	v_mov_b32_e32 v30, v88
	v_mov_b32_e32 v31, v88
	v_mov_b32_e32 v32, v88
	v_mov_b32_e32 v33, v88
	v_mov_b32_e32 v4, v88
	v_mov_b32_e32 v5, v88
	v_mov_b32_e32 v6, v88
	v_mov_b32_e32 v7, v88
	v_mov_b32_e32 v8, v88
	v_mov_b32_e32 v9, v88
	v_mov_b32_e32 v10, v88
	v_mov_b32_e32 v11, v88
	v_mov_b32_e32 v12, v88
	v_mov_b32_e32 v13, v88
	v_mov_b32_e32 v14, v88
	v_mov_b32_e32 v15, v88
	v_mov_b32_e32 v16, v88
	v_mul_u32_u24_e32 v204, 0x90, v80
	global_load_dwordx4 v[66:69], v[2:3], off
	global_load_dwordx4 v[70:73], v[74:75], off
	v_mov_b32_e32 v2, 0
	v_mov_b32_e32 v3, v88
	v_cmp_gt_u32_e64 s[66:67], 32, v84
	v_mul_u32_u24_e32 v86, 3, v202
	v_add3_u32 v89, v34, v35, v181
	v_add3_u32 v87, s74, v36, v37
	v_cndmask_b32_e32 v91, 0, v17, vcc
	v_mov_b32_e32 v17, v88
	s_waitcnt vmcnt(1)
	ds_write_b128 v198, v[66:69]
	s_waitcnt vmcnt(0)
	ds_write2_b64 v199, v[70:71], v[72:73] offset0:128 offset1:130
	s_waitcnt lgkmcnt(0)
	s_barrier
	s_branch .LBB0_493
